# P5 tile seams: mid-K row-stat loads no longer drain the DMA queue, epilogue entry and accumulator reset waits counted
# baseline (speedup 1.0000x reference)
; #define PG8_WAIT_V(n) asm volatile("s_waitcnt vmcnt(" #n ")" ::: "memory")
; template <class Epi, class Sched, bool ALIGN_EPI>
; __device__ __forceinline__ void gemm_phase(PG8_LAS unsigned char* lds, const Gemm g, const Sched& S, const Epi& E) {
;     ...
;         const char* nA = has_next ? (const char*)g.A + (size_t)nxt.pm * tsA : cA; const char* nB = has_next ? (const char*)g.Bt + (size_t)nxt.pn * tsB : cB;
;         for (int t = 0; t < nt; t += 2) {
;             const bool last = (t == nt - 2);
;             const char* a1 = cA + (size_t)(t + 1) * kstep;
;             const char* a2 = last ? nA : cA + (size_t)(t + 2) * kstep; const char* b2 = last ? nB : cB + (size_t)(t + 2) * kstep;
;             const char* a3 = a2 + kstep; const char* b3 = b2 + kstep;
;             if constexpr (Epi::MID_T >= 0) { if (t == Epi::MID_T) E.mid(acc, cur, wr, fr); }
;             PG8_LDB(B0, 0, 0); PG8_LDB(B1, 0, 1); PG8_SCHED; PG8_LDA(At, 0, 0); PG8_STAGE(PG8_SA(1, 1), a1 + hsA, voffA);
;             PG8_WAIT_V(8); PG8_WAIT_L(0); PG8_BAR; PG8_MMA(0, 0, At, B0); PG8_MMA(0, 1, At, B1); PG8_BAR; PG8_SCHED;
;             PG8_LDA(At, 0, 1); PG8_STAGE(PG8_SB(0, 0), b2, voffB); PG8_STAGE(PG8_SB(0, 1), b2 + hsB, voffB); PG8_STAGE(PG8_SA(0, 0), a2, voffA);
;             PG8_WAIT_V(8); PG8_WAIT_L(0); PG8_BAR; PG8_MMA(1, 0, At, B0); PG8_MMA(1, 1, At, B1); PG8_BAR; PG8_SCHED;
;             PG8_LDB(B0, 1, 0); PG8_LDB(B1, 1, 1); PG8_SCHED; PG8_LDA(At, 1, 0); PG8_STAGE(PG8_SA(0, 1), a2 + hsA, voffA);
;             PG8_WAIT_V(8); PG8_WAIT_L(0); PG8_BAR; PG8_MMA(0, 0, At, B0); PG8_MMA(0, 1, At, B1); PG8_BAR; PG8_SCHED;
;             PG8_LDA(At, 1, 1); PG8_STAGE(PG8_SB(1, 0), b3, voffB); PG8_STAGE(PG8_SB(1, 1), b3 + hsB, voffB); PG8_STAGE(PG8_SA(1, 0), a3, voffA);
;             PG8_WAIT_V(8); PG8_WAIT_L(0); PG8_BAR; PG8_MMA(1, 0, At, B0); PG8_MMA(1, 1, At, B1); PG8_BAR; PG8_SCHED;
;         }
;         if constexpr (ALIGN_EPI) { if (wr == 0) PG8_BAR; }
;         E(acc, cur, wr, wc, fr, fq);
;         if (!has_next) break;
; #pragma unroll
;         for (int a = 0; a < 2; ++a)
; #pragma unroll
;             for (int b = 0; b < 2; ++b)
; #pragma unroll
;                 for (int m = 0; m < 4; ++m)
; #pragma unroll
;                     for (int n = 0; n < 2; ++n) acc[a][b][m][n] = (f32x4){0.f, 0.f, 0.f, 0.f};
;         cur = nxt; cA = nA; cB = nB; ++ui;
.LBB0_939:
	s_ashr_i32 s31, s30, 31
	s_lshl_b64 s[34:35], s[30:31], 19
	s_add_u32 s34, s6, s34
	s_addc_u32 s35, s7, s35
	s_and_b64 s[36:37], s[0:1], exec
	s_cselect_b32 s31, s35, s43
	s_cselect_b32 s60, s34, s42
	s_ashr_i32 s17, s16, 31
	s_lshl_b64 s[36:37], s[16:17], 19
	s_add_u32 s36, s19, s36
	s_addc_u32 s37, s33, s37
	s_and_b64 s[62:63], s[0:1], exec
	s_cselect_b32 s17, s37, s41
	s_cselect_b32 s61, s36, s40
	v_lshl_add_u32 v157, s38, 8, v144
	s_add_u32 s38, s42, 0x40080
	s_addc_u32 s39, s43, 0
	s_add_u32 s62, s40, 0x100
	v_mov_b32_e32 v0, 0
	s_addc_u32 s63, s41, 0
	s_mov_b32 s64, -2
	v_mov_b32_e32 v1, v0
	v_mov_b32_e32 v2, v0
	v_mov_b32_e32 v3, v0
	v_mov_b32_e32 v8, v0
	v_mov_b32_e32 v9, v0
	v_mov_b32_e32 v10, v0
	v_mov_b32_e32 v11, v0
	v_mov_b32_e32 v16, v0
	v_mov_b32_e32 v17, v0
	v_mov_b32_e32 v18, v0
	v_mov_b32_e32 v19, v0
	v_mov_b32_e32 v24, v0
	v_mov_b32_e32 v25, v0
	v_mov_b32_e32 v26, v0
	v_mov_b32_e32 v27, v0
	v_mov_b32_e32 v32, v0
	v_mov_b32_e32 v33, v0
	v_mov_b32_e32 v34, v0
	v_mov_b32_e32 v35, v0
	v_mov_b32_e32 v40, v0
	v_mov_b32_e32 v41, v0
	v_mov_b32_e32 v42, v0
	v_mov_b32_e32 v43, v0
	v_mov_b32_e32 v48, v0
	v_mov_b32_e32 v49, v0
	v_mov_b32_e32 v50, v0
	v_mov_b32_e32 v51, v0
	v_mov_b32_e32 v56, v0
	v_mov_b32_e32 v57, v0
	v_mov_b32_e32 v58, v0
	v_mov_b32_e32 v59, v0
	v_mov_b32_e32 v4, v0
	v_mov_b32_e32 v5, v0
	v_mov_b32_e32 v6, v0
	v_mov_b32_e32 v7, v0
	v_mov_b32_e32 v12, v0
	v_mov_b32_e32 v13, v0
	v_mov_b32_e32 v14, v0
	v_mov_b32_e32 v15, v0
	v_mov_b32_e32 v20, v0
	v_mov_b32_e32 v21, v0
	v_mov_b32_e32 v22, v0
	v_mov_b32_e32 v23, v0
	v_mov_b32_e32 v28, v0
	v_mov_b32_e32 v29, v0
	v_mov_b32_e32 v30, v0
	v_mov_b32_e32 v31, v0
	v_mov_b32_e32 v36, v0
	v_mov_b32_e32 v37, v0
	v_mov_b32_e32 v38, v0
	v_mov_b32_e32 v39, v0
	v_mov_b32_e32 v44, v0
	v_mov_b32_e32 v45, v0
	v_mov_b32_e32 v46, v0
	v_mov_b32_e32 v47, v0
	v_mov_b32_e32 v52, v0
	v_mov_b32_e32 v53, v0
	v_mov_b32_e32 v54, v0
	v_mov_b32_e32 v55, v0
	v_mov_b32_e32 v60, v0
	v_mov_b32_e32 v61, v0
	v_mov_b32_e32 v62, v0
	v_mov_b32_e32 v63, v0
	v_mov_b32_e32 v64, v0
	v_mov_b32_e32 v65, v0
	v_mov_b32_e32 v66, v0
	v_mov_b32_e32 v67, v0
	v_mov_b32_e32 v72, v0
	v_mov_b32_e32 v73, v0
	v_mov_b32_e32 v74, v0
	v_mov_b32_e32 v75, v0
	v_mov_b32_e32 v80, v0
	v_mov_b32_e32 v81, v0
	v_mov_b32_e32 v82, v0
	v_mov_b32_e32 v83, v0
	v_mov_b32_e32 v88, v0
	v_mov_b32_e32 v89, v0
	v_mov_b32_e32 v90, v0
	v_mov_b32_e32 v91, v0
	v_mov_b32_e32 v96, v0
	v_mov_b32_e32 v97, v0
	v_mov_b32_e32 v98, v0
	v_mov_b32_e32 v99, v0
	v_mov_b32_e32 v104, v0
	v_mov_b32_e32 v105, v0
	v_mov_b32_e32 v106, v0
	v_mov_b32_e32 v107, v0
	v_mov_b32_e32 v112, v0
	v_mov_b32_e32 v113, v0
	v_mov_b32_e32 v114, v0
	v_mov_b32_e32 v115, v0
	v_mov_b32_e32 v120, v0
	v_mov_b32_e32 v121, v0
	v_mov_b32_e32 v122, v0
	v_mov_b32_e32 v123, v0
	v_mov_b32_e32 v68, v0
	v_mov_b32_e32 v69, v0
	v_mov_b32_e32 v70, v0
	v_mov_b32_e32 v71, v0
	v_mov_b32_e32 v76, v0
	v_mov_b32_e32 v77, v0
	v_mov_b32_e32 v78, v0
	v_mov_b32_e32 v79, v0
	v_mov_b32_e32 v84, v0
	v_mov_b32_e32 v85, v0
	v_mov_b32_e32 v86, v0
	v_mov_b32_e32 v87, v0
	v_mov_b32_e32 v92, v0
	v_mov_b32_e32 v93, v0
	v_mov_b32_e32 v94, v0
	v_mov_b32_e32 v95, v0
	v_mov_b32_e32 v100, v0
	v_mov_b32_e32 v101, v0
	v_mov_b32_e32 v102, v0
	v_mov_b32_e32 v103, v0
	v_mov_b32_e32 v108, v0
	v_mov_b32_e32 v109, v0
	v_mov_b32_e32 v110, v0
	v_mov_b32_e32 v111, v0
	v_mov_b32_e32 v116, v0
	v_mov_b32_e32 v117, v0
	v_mov_b32_e32 v118, v0
	v_mov_b32_e32 v119, v0
	v_mov_b32_e32 v124, v0
	v_mov_b32_e32 v125, v0
	v_mov_b32_e32 v126, v0
	v_mov_b32_e32 v127, v0
	s_branch .LBB0_941

; template <class Epi, class Sched, bool ALIGN_EPI>
; __device__ __forceinline__ void gemm_phase(PG8_LAS unsigned char* lds, const Gemm g, const Sched& S, const Epi& E) {
;     ...
;             if constexpr (Epi::MID_T >= 0) { if (t == Epi::MID_T) E.mid(acc, cur, wr, fr); }
;     __device__ __forceinline__ void mid(f32x4 (&)[2][2][4][2], const Unit& u, int wr, int fr) const {
;         int row0 = u.pm * BM + wr * 64 + fr; asm volatile("" : "+v"(row0));
; #pragma unroll
;         for (int ai = 0; ai < 2; ++ai)
; #pragma unroll
;             for (int m = 0; m < 4; ++m) pre[ai * 4 + m] = rs1[row0 + ai * HALF + m * 16];
;     }
.LBB0_941:
	s_cmp_eq_u32 s64, 12
	s_cselect_b64 s[40:41], -1, 0
	s_cmp_lg_u32 s64, 12
	s_cbranch_scc1 .LBB0_940
	v_mov_b32_e32 v150, v157
	s_nop 0
	v_ashrrev_i32_e32 v151, 31, v150
	v_lshl_add_u64 v[158:159], v[150:151], 2, s[10:11]
	global_load_dword v156, v[158:159], off
	global_load_dword v155, v[158:159], off offset:64
	global_load_dword v154, v[158:159], off offset:128
	global_load_dword v153, v[158:159], off offset:192
	global_load_dword v152, v[158:159], off offset:512
	global_load_dword v151, v[158:159], off offset:576
	global_load_dword v150, v[158:159], off offset:640
	global_load_dword v149, v[158:159], off offset:704
	s_branch .LBB0_940
